# v34 + partial Y counter of the own GEMM2 tile sampled at pop look-ahead points; GEMM2 start poll skipped when it shows 10, fresh YRDY sample loaded asynchronously for the mid-loop check
# speedup vs baseline: 1.0023x; 1.0023x over previous
.LBB0_151:
	v_readlane_b32 s0, v252, 0
	s_mov_b32 s78, s0
	v_readlane_b32 s0, v254, 5
	s_ashr_i32 s2, s0, 2
	s_and_b32 s3, s0, 3
	s_lshl_b32 s0, s2, 6
	s_ashr_i32 s1, s0, 31
	v_writelane_b32 v254, s0, 8
	s_lshl_b32 s79, s2, 5
	s_lshl_b32 s4, s2, 9
	v_writelane_b32 v254, s1, 9
	s_mov_b32 s0, s2
	v_writelane_b32 v254, s0, 10
	s_mov_b64 s[10:11], -1
	s_mov_b64 s[12:13], 0
	v_writelane_b32 v254, s1, 11
	s_lshl_b32 s0, s2, 4
	v_writelane_b32 v254, s0, 12
	v_writelane_b32 v254, s73, 13
	v_writelane_b32 v254, s80, 14
	s_cmp_lt_i32 s3, 2
	s_mov_b64 s[8:9], 0
	v_writelane_b32 v254, s81, 15
	s_cbranch_scc1 .LBB0_359
	s_cmp_eq_u32 s3, 2
	s_mov_b64 s[8:9], -1
	s_cbranch_scc0 .LBB0_358
	v_writelane_b32 v254, s3, 16
	v_cmp_eq_u32_e64 s[42:43], 0, v218
	v_readlane_b32 s0, v254, 8
	v_readlane_b32 s1, v254, 9
	s_lshl_b64 s[2:3], s[0:1], 2
	v_readlane_b32 s0, v252, 13
	s_add_u32 s2, s0, s2
	v_readlane_b32 s0, v252, 14
	s_addc_u32 s3, s0, s3
	v_writelane_b32 v254, s2, 17
	s_nop 1
	v_writelane_b32 v254, s3, 18
	s_nop 0
	v_readlane_b32 s0, v254, 10
	v_readlane_b32 s1, v254, 11
	s_lshl_b32 s0, s0, 3
	s_ashr_i32 s1, s0, 31
	v_writelane_b32 v254, s0, 19
	s_nop 1
	v_writelane_b32 v254, s1, 20
	s_add_u32 s0, s88, 0x4800000
	v_writelane_b32 v254, s0, 21
	s_addc_u32 s0, s89, 0
	v_writelane_b32 v254, s0, 23
	s_add_u32 s0, s88, 0x4e00000
	v_writelane_b32 v254, s0, 24
	s_addc_u32 s0, s89, 0
	v_writelane_b32 v254, s0, 25
	s_add_u32 s0, s88, 0x5000000
	v_writelane_b32 v254, s0, 26
	s_addc_u32 s0, s89, 0
	v_writelane_b32 v254, s0, 27
	s_add_u32 s0, s88, 0x6900000
	v_writelane_b32 v254, s0, 28
	s_addc_u32 s0, s89, 0
	v_writelane_b32 v254, s0, 30
	s_add_u32 s0, s88, 0x8200000
	v_writelane_b32 v254, s0, 31
	s_addc_u32 s0, s89, 0
	v_writelane_b32 v254, s0, 33
	s_add_u32 s0, s88, 0x8e00000
	v_writelane_b32 v254, s0, 34
	s_addc_u32 s0, s89, 0
	v_writelane_b32 v254, s0, 36
	s_add_u32 s0, s88, 0x5800000
	v_writelane_b32 v254, s0, 37
	s_addc_u32 s0, s89, 0
	v_writelane_b32 v254, s0, 39
	s_add_u32 s0, s88, 0xa00000
	v_writelane_b32 v254, s0, 41
	s_addc_u32 s0, s89, 0
	v_writelane_b32 v254, s0, 43
	s_add_u32 s0, s88, 0x400000
	v_writelane_b32 v254, s0, 44
	s_addc_u32 s0, s89, 0
	v_writelane_b32 v254, s0, 46
	s_add_u32 s0, s88, 0x600000
	v_writelane_b32 v254, s0, 48
	s_addc_u32 s0, s89, 0
	v_writelane_b32 v254, s0, 50
	s_add_u32 s0, s88, 0x3c00000
	v_writelane_b32 v254, s0, 52
	s_addc_u32 s0, s89, 0
	v_writelane_b32 v254, s0, 53
	s_add_u32 s0, s88, 0x4000000
	v_writelane_b32 v254, s0, 54
	s_addc_u32 s0, s89, 0
	v_writelane_b32 v254, s0, 56
	s_add_u32 s0, s88, 0x4400000
	v_writelane_b32 v254, s0, 57
	s_addc_u32 s0, s89, 0
	s_cmp_eq_u32 s73, 0
	v_writelane_b32 v254, s0, 58
	s_cselect_b64 s[12:13], -1, 0
	s_add_u32 s0, s88, 0x8000
	v_writelane_b32 v254, s0, 59
	s_addc_u32 s0, s89, 0
	s_add_u32 s14, s88, 0x4200
	v_writelane_b32 v254, s0, 60
	s_addc_u32 s15, s89, 0
	s_and_b32 s0, s73, 3
	s_ashr_i32 s2, s73, 2
	s_lshl_b32 s1, s2, 5
	s_lshl_b32 s2, s2, 12
	s_lshl_b32 s3, s0, 10
	s_or_b32 s80, s2, s3
	s_lshl_b32 s51, s73, 5
	s_lshl_b32 s5, s0, 12
	s_addk_i32 s80, 0x3000
	s_lshl_b32 s16, s73, 10
	s_lshl_b32 s10, s73, 3
	s_and_b32 s6, s51, 32
	s_add_i32 s7, s5, s1
	s_add_i32 s17, s16, 0
	s_add_i32 s38, s80, 0
	s_bfe_u32 s2, s73, 0x10001
	s_cmp_eq_u32 s2, 0
	s_cselect_b64 s[8:9], -1, 0
	v_writelane_b32 v254, s8, 61
	s_add_u32 s5, s88, 0xa200
	s_mov_b32 s81, s1
	v_writelane_b32 v254, s9, 62
	v_writelane_b32 v254, s5, 63
	s_addc_u32 s5, s89, 0
	s_cmp_lt_i32 s73, 4
	v_writelane_b32 v255, s5, 0
	s_cselect_b64 s[8:9], -1, 0
	v_writelane_b32 v255, s8, 2
	s_lshl_b32 s2, s2, 16
	v_readlane_b32 s5, v252, 15
	v_writelane_b32 v255, s9, 3
	s_add_u32 s2, s5, s2
	v_readlane_b32 s5, v252, 16
	s_addc_u32 s5, s5, 0
	v_writelane_b32 v255, s6, 4
	s_lshl_b32 s6, s6, 8
	s_add_u32 s2, s2, s6
	v_writelane_b32 v255, s2, 6
	s_addc_u32 s2, s5, 0
	v_writelane_b32 v255, s2, 7
	s_add_u32 s2, s88, 0x300000
	v_writelane_b32 v255, s2, 8
	s_addc_u32 s2, s89, 0
	s_add_u32 s39, s88, 0x1800
	s_addc_u32 s8, s89, 0
	v_writelane_b32 v255, s2, 9
	s_add_u32 s2, s88, 0x9000
	v_writelane_b32 v255, s2, 10
	s_addc_u32 s2, s89, 0
	v_writelane_b32 v255, s2, 11
	s_lshl_b32 s2, s73, 9
	s_add_i32 s2, s2, 0
	s_add_i32 s2, s2, 0x21800
	v_writelane_b32 v255, s2, 12
	s_add_u32 s18, s88, 0x5900000
	s_mul_i32 s2, s73, 0x2200
	s_addc_u32 s19, s89, 0
	s_add_i32 s9, s2, 0
	s_add_u32 s26, s88, 0x7200000
	s_addc_u32 s27, s89, 0
	s_lshl_b32 s2, s0, 11
	v_writelane_b32 v255, s7, 13
	s_sub_i32 s5, s7, s2
	v_writelane_b32 v255, s5, 14
	s_lshl_b32 s5, s73, 7
	s_add_i32 s6, s5, 0
	s_add_i32 s6, s6, 0x22800
	s_add_u32 s5, s88, 0x9800
	v_writelane_b32 v255, s5, 15
	s_addc_u32 s5, s89, 0
	v_writelane_b32 v255, s5, 16
	s_add_u32 s5, s88, 0x8800
	v_writelane_b32 v255, s5, 17
	s_addc_u32 s5, s89, 0
	v_writelane_b32 v255, s5, 18
	s_lshl_b32 s5, s0, 4
	s_add_i32 s3, s3, 0
	v_writelane_b32 v255, s5, 19
	s_add_i32 s7, s3, 0x2000
	v_writelane_b32 v255, s3, 20
	s_add_u32 s3, s88, 0x4410000
	v_writelane_b32 v255, s3, 22
	s_addc_u32 s3, s89, 0
	v_writelane_b32 v255, s3, 23
	s_add_u32 s3, s88, 0x4010000
	v_writelane_b32 v255, s3, 24
	s_addc_u32 s3, s89, 0
	v_writelane_b32 v255, s3, 25
	s_lshl_b32 s3, s73, 11
	v_writelane_b32 v255, s3, 26
	s_add_i32 s2, s2, s1
	v_writelane_b32 v255, s2, 27
	s_lshl_b32 s2, s0, 9
	s_mulk_i32 s0, 0x3000
	v_writelane_b32 v255, s2, 29
	s_add_i32 s0, s0, s1
	v_writelane_b32 v255, s0, 30
	v_and_b32_e32 v174, 31, v205
	v_add_u32_e32 v174, s79, v174
	v_lshlrev_b32_e32 v174, 4, v174
	v_lshrrev_b32_e32 v175, 5, v205
	v_lshl_add_u32 v174, v175, 12, v174
	v_mov_b32_e32 v175, 0
	v_readlane_b32 s100, v254, 59
	v_readlane_b32 s101, v254, 60
	s_nop 1
	v_lshl_add_u64 v[174:175], s[100:101], 0, v[174:175]
	v_readlane_b32 s100, v254, 17
	v_readlane_b32 s101, v254, 18
	s_nop 3
	v_mov_b32_e32 v182, s100
	v_mov_b32_e32 v183, s101
	s_and_b32 s100, s78, 31
	s_add_i32 s100, s100, s79
	s_lshl_b32 s100, s100, 4
	s_add_u32 s100, s39, s100
	s_addc_u32 s101, s8, 0
	v_mov_b32_e32 v176, s100
	v_mov_b32_e32 v177, s101
	s_mov_b64 s[100:101], exec
	s_mov_b64 exec, s[12:13]
	global_load_dword v184, v[174:175], off sc1
	global_load_dword v173, v[176:177], off offset:4 sc1
	s_mov_b64 exec, s[42:43]
	global_atomic_add v221, v[182:183], v181, off sc0
	s_mov_b64 exec, s[100:101]
	s_branch .LBB0_156

.LBB0_203:
	v_add_u32_e32 v56, 0, v112
	s_waitcnt vmcnt(0)
	s_mov_b64 s[100:101], exec
	s_mov_b64 exec, s[12:13]
	global_load_dword v184, v[174:175], off sc1
	global_load_dword v173, v[176:177], off offset:4 sc1
	s_mov_b64 exec, s[42:43]
	global_atomic_add v221, v[182:183], v181, off sc0
	s_mov_b64 exec, s[100:101]
	s_barrier
	v_add_u32_e32 v36, v56, v113
	ds_read_b128 v[32:35], v36 offset:4096
	ds_read_b128 v[48:51], v36
	v_add_u32_e32 v57, v56, v114
	ds_read_b128 v[52:55], v57 offset:4096
	ds_read_b128 v[94:97], v57
	v_add_u32_e32 v58, v56, v111
	s_waitcnt lgkmcnt(3)
	v_mfma_f32_32x32x16_bf16 v[32:47], v[32:35], v[76:79], 0
	v_add_u32_e32 v56, v56, v110
	v_readlane_b32 s0, v255, 2
	v_readlane_b32 s1, v255, 3
	s_andn2_b64 vcc, exec, s[0:1]
	ds_read_b128 v[100:103], v58
	s_waitcnt lgkmcnt(2)
	v_mfma_f32_32x32x16_bf16 v[32:47], v[52:55], v[72:75], v[32:47]
	ds_read_b128 v[52:55], v58 offset:4096
	s_waitcnt lgkmcnt(0)
	v_mfma_f32_32x32x16_bf16 v[32:47], v[52:55], v[68:71], v[32:47]
	ds_read_b128 v[52:55], v56 offset:4096
	ds_read_b128 v[110:113], v56
	s_waitcnt lgkmcnt(1)
	v_mfma_f32_32x32x16_bf16 v[32:47], v[52:55], v[64:67], v[32:47]
	v_add_u32_e32 v52, 0, v108
	v_add3_u32 v106, v52, v109, v106
	ds_read_b64_tr_b16 v[90:91], v106 offset:12288
	ds_read_b64_tr_b16 v[92:93], v106 offset:12800
	ds_read_b64_tr_b16 v[82:83], v106 offset:13312
	ds_read_b64_tr_b16 v[84:85], v106 offset:13824
	v_mfma_f32_32x32x16_bf16 v[48:63], v[48:51], v[76:79], 0
	v_add_u32_e32 v76, 0xc0, v107
	v_cvt_f32_i32_e32 v107, v76
	ds_read_b64_tr_b16 v[86:87], v106 offset:14336
	ds_read_b64_tr_b16 v[88:89], v106 offset:14848
	ds_read_b64_tr_b16 v[76:77], v106 offset:15360
	ds_read_b64_tr_b16 v[78:79], v106 offset:15872
	v_mfma_f32_32x32x16_bf16 v[48:63], v[94:97], v[72:75], v[48:63]
	v_add_f32_e32 v74, 0x41d00000, v107
	v_add_f32_e32 v75, 0x41d80000, v107
	v_add_f32_e32 v72, 0x42000000, v74
	v_add_f32_e32 v73, 0x42000000, v75
	v_fma_f32 v72, v72, v104, v105
	v_fma_f32 v73, v73, v104, v105
	v_exp_f32_e32 v72, v72
	v_mfma_f32_32x32x16_bf16 v[48:63], v[100:103], v[68:71], v[48:63]
	v_exp_f32_e32 v73, v73
	s_nop 0
	v_pk_mul_f32 v[68:69], v[46:47], v[72:73]
	v_fma_f32 v46, v74, v104, v105
	v_fma_f32 v47, v75, v104, v105
	s_waitcnt lgkmcnt(8)
	v_mfma_f32_32x32x16_bf16 v[48:63], v[110:113], v[64:67], v[48:63]
	v_exp_f32_e32 v46, v46
	v_exp_f32_e32 v47, v47
	v_add_f32_e32 v65, 0x41c80000, v107
	v_add_f32_e32 v67, 0x41980000, v107
	v_add_f32_e32 v74, 0x41200000, v107
	v_add_f32_e32 v75, 0x41300000, v107
	v_add_f32_e32 v72, 0x42000000, v74
	s_nop 4
	v_pk_mul_f32 v[62:63], v[62:63], v[46:47]
	v_add_f32_e32 v46, 0x41c00000, v107
	v_add_f32_e32 v47, 0x42000000, v46
	v_fma_f32 v47, v47, v104, v105
	v_exp_f32_e32 v64, v47
	v_fma_f32 v46, v46, v104, v105
	v_fma_f32 v47, v65, v104, v105
	v_exp_f32_e32 v46, v46
	v_exp_f32_e32 v47, v47
	v_add_f32_e32 v73, 0x42000000, v75
	v_fma_f32 v74, v74, v104, v105
	v_fma_f32 v75, v75, v104, v105
	v_pk_mul_f32 v[60:61], v[60:61], v[46:47]
	v_add_f32_e32 v46, 0x41900000, v107
	v_add_f32_e32 v47, 0x42000000, v46
	v_fma_f32 v47, v47, v104, v105
	v_exp_f32_e32 v66, v47
	v_fma_f32 v46, v46, v104, v105
	v_fma_f32 v47, v67, v104, v105
	v_exp_f32_e32 v46, v46
	v_exp_f32_e32 v47, v47
	v_exp_f32_e32 v74, v74
	v_exp_f32_e32 v75, v75
	v_fma_f32 v72, v72, v104, v105
	v_pk_mul_f32 v[58:59], v[58:59], v[46:47]
	v_add_f32_e32 v46, 0x41800000, v107
	v_add_f32_e32 v47, 0x42000000, v46
	v_fma_f32 v47, v47, v104, v105
	v_exp_f32_e32 v70, v47
	v_add_f32_e32 v47, 0x41880000, v107
	v_add_f32_e32 v71, 0x42000000, v47
	v_fma_f32 v46, v46, v104, v105
	v_fma_f32 v47, v47, v104, v105
	v_exp_f32_e32 v46, v46
	v_exp_f32_e32 v47, v47
	v_pk_mul_f32 v[54:55], v[54:55], v[74:75]
	v_add_f32_e32 v74, 2.0, v107
	v_fma_f32 v73, v73, v104, v105
	v_add_f32_e32 v75, 0x42000000, v74
	v_exp_f32_e32 v72, v72
	v_exp_f32_e32 v73, v73
	v_fma_f32 v96, v75, v104, v105
	v_add_f32_e32 v75, 0x40400000, v107
	v_pk_mul_f32 v[56:57], v[56:57], v[46:47]
	v_add_f32_e32 v46, 0x41000000, v107
	v_add_f32_e32 v94, 0x42000000, v75
	v_add_f32_e32 v47, 0x42000000, v46
	v_fma_f32 v97, v94, v104, v105
	v_add_f32_e32 v94, 0, v107
	v_fma_f32 v47, v47, v104, v105
	v_add_f32_e32 v95, 0x42000000, v94
	v_pk_mul_f32 v[38:39], v[38:39], v[72:73]
	v_exp_f32_e32 v72, v47
	v_add_f32_e32 v47, 0x41100000, v107
	v_fma_f32 v100, v95, v104, v105
	v_add_f32_e32 v95, 1.0, v107
	v_add_f32_e32 v65, 0x42000000, v65
	v_add_f32_e32 v67, 0x42000000, v67
	v_add_f32_e32 v73, 0x42000000, v47
	v_add_f32_e32 v101, 0x42000000, v95
	v_fma_f32 v65, v65, v104, v105
	v_fma_f32 v67, v67, v104, v105
	v_fma_f32 v71, v71, v104, v105
	v_fma_f32 v73, v73, v104, v105
	v_fma_f32 v46, v46, v104, v105
	v_fma_f32 v47, v47, v104, v105
	v_fma_f32 v74, v74, v104, v105
	v_fma_f32 v75, v75, v104, v105
	v_fma_f32 v101, v101, v104, v105
	v_fma_f32 v94, v94, v104, v105
	v_fmac_f32_e32 v105, v95, v104
	v_exp_f32_e32 v46, v46
	v_exp_f32_e32 v47, v47
	v_exp_f32_e32 v94, v94
	v_exp_f32_e32 v95, v105
	v_exp_f32_e32 v74, v74
	v_exp_f32_e32 v75, v75
	v_exp_f32_e32 v73, v73
	v_pk_mul_f32 v[52:53], v[52:53], v[46:47]
	v_exp_f32_e32 v96, v96
	v_pk_mul_f32 v[46:47], v[48:49], v[94:95]
	v_cvt_pk_bf16_f32 v49, v54, v55
	v_exp_f32_e32 v97, v97
	v_exp_f32_e32 v54, v100
	v_exp_f32_e32 v55, v101
	v_exp_f32_e32 v67, v67
	v_exp_f32_e32 v71, v71
	v_pk_mul_f32 v[50:51], v[50:51], v[74:75]
	v_cvt_pk_bf16_f32 v46, v46, v47
	v_cvt_pk_bf16_f32 v47, v50, v51
	v_cvt_pk_bf16_f32 v48, v52, v53
	v_pk_mul_f32 v[36:37], v[36:37], v[72:73]
	v_pk_mul_f32 v[34:35], v[34:35], v[96:97]
	v_pk_mul_f32 v[32:33], v[32:33], v[54:55]
	v_pk_mul_f32 v[42:43], v[42:43], v[66:67]
	v_cvt_pk_bf16_f32 v32, v32, v33
	v_cvt_pk_bf16_f32 v33, v34, v35
	v_cvt_pk_bf16_f32 v34, v36, v37
	v_pk_mul_f32 v[36:37], v[40:41], v[70:71]
	v_cvt_pk_bf16_f32 v50, v56, v57
	v_cvt_pk_bf16_f32 v36, v36, v37
	v_cvt_pk_bf16_f32 v37, v42, v43
	ds_read_b64_tr_b16 v[40:41], v106 offset:16384
	ds_read_b64_tr_b16 v[42:43], v106 offset:16896
	ds_read_b64_tr_b16 v[54:55], v106 offset:17408
	ds_read_b64_tr_b16 v[56:57], v106 offset:17920
	s_waitcnt lgkmcnt(10)
	v_mfma_f32_32x32x16_bf16 v[16:31], v[46:49], v[90:93], v[16:31]
	v_cvt_pk_bf16_f32 v51, v58, v59
	v_cvt_pk_bf16_f32 v52, v60, v61
	v_cvt_pk_bf16_f32 v53, v62, v63
	v_exp_f32_e32 v65, v65
	v_cvt_pk_bf16_f32 v35, v38, v39
	v_pk_mul_f32 v[38:39], v[44:45], v[64:65]
	s_waitcnt lgkmcnt(2)
	v_mfma_f32_32x32x16_bf16 v[0:15], v[46:49], v[40:43], v[0:15]
	ds_read_b64_tr_b16 v[40:41], v106 offset:18432
	ds_read_b64_tr_b16 v[42:43], v106 offset:18944
	ds_read_b64_tr_b16 v[44:45], v106 offset:19456
	ds_read_b64_tr_b16 v[46:47], v106 offset:19968
	v_cvt_pk_bf16_f32 v38, v38, v39
	v_cvt_pk_bf16_f32 v39, v68, v69
	v_mfma_f32_32x32x16_bf16 v[16:31], v[50:53], v[82:85], v[16:31]
	s_waitcnt lgkmcnt(4)
	v_mfma_f32_32x32x16_bf16 v[0:15], v[50:53], v[54:57], v[0:15]
	v_mfma_f32_32x32x16_bf16 v[16:31], v[32:35], v[86:89], v[16:31]
	s_waitcnt lgkmcnt(2)
	v_mfma_f32_32x32x16_bf16 v[0:15], v[32:35], v[40:43], v[0:15]
	v_mfma_f32_32x32x16_bf16 v[16:31], v[36:39], v[76:79], v[16:31]
	s_waitcnt lgkmcnt(0)
	v_mfma_f32_32x32x16_bf16 v[0:15], v[36:39], v[44:47], v[0:15]
	s_cbranch_vccnz .LBB0_205
	s_lshl_b32 s0, s2, 3
	s_or_b32 s36, s0, s3
	s_ashr_i32 s37, s36, 31
	s_lshl_b64 s[36:37], s[36:37], 14
	v_readlane_b32 s0, v255, 6
	s_add_u32 s36, s0, s36
	v_readlane_b32 s0, v255, 7
	v_lshlrev_b32_e32 v32, 2, v80
	s_addc_u32 s37, s0, s37
	v_ashrrev_i32_e32 v99, 31, v98
	v_ashrrev_i32_e32 v33, 31, v32
	v_or_b32_e32 v38, 1, v32
	v_lshl_add_u64 v[34:35], v[98:99], 2, s[36:37]
	v_lshlrev_b64 v[36:37], 8, v[32:33]
	v_ashrrev_i32_e32 v39, 31, v38
	v_lshl_add_u64 v[36:37], v[34:35], 0, v[36:37]
	v_lshlrev_b64 v[38:39], 8, v[38:39]
	global_store_dword v[36:37], v16, off
	v_lshl_add_u64 v[38:39], v[34:35], 0, v[38:39]
	v_or_b32_e32 v16, 2, v32
	global_store_dword v[38:39], v17, off
	v_ashrrev_i32_e32 v17, 31, v16
	v_or_b32_e32 v40, 3, v32
	v_lshlrev_b64 v[16:17], 8, v[16:17]
	v_ashrrev_i32_e32 v41, 31, v40
	v_lshl_add_u64 v[16:17], v[34:35], 0, v[16:17]
	v_lshlrev_b64 v[40:41], 8, v[40:41]
	global_store_dword v[16:17], v18, off
	v_lshl_add_u64 v[40:41], v[34:35], 0, v[40:41]
	v_add_u32_e32 v18, 8, v32
	global_store_dword v[40:41], v19, off
	v_ashrrev_i32_e32 v19, 31, v18
	v_add_u32_e32 v42, 9, v32
	v_lshlrev_b64 v[18:19], 8, v[18:19]
	v_ashrrev_i32_e32 v43, 31, v42
	v_lshl_add_u64 v[18:19], v[34:35], 0, v[18:19]
	v_lshlrev_b64 v[42:43], 8, v[42:43]
	global_store_dword v[18:19], v20, off
	v_lshl_add_u64 v[42:43], v[34:35], 0, v[42:43]
	v_add_u32_e32 v20, 10, v32
	global_store_dword v[42:43], v21, off
	v_ashrrev_i32_e32 v21, 31, v20
	v_add_u32_e32 v44, 11, v32
	v_lshlrev_b64 v[20:21], 8, v[20:21]
	v_ashrrev_i32_e32 v45, 31, v44
	v_lshl_add_u64 v[20:21], v[34:35], 0, v[20:21]
	v_lshlrev_b64 v[44:45], 8, v[44:45]
	global_store_dword v[20:21], v22, off
	v_lshl_add_u64 v[44:45], v[34:35], 0, v[44:45]
	v_add_u32_e32 v22, 16, v32
	global_store_dword v[44:45], v23, off
	v_ashrrev_i32_e32 v23, 31, v22
	v_add_u32_e32 v46, 17, v32
	v_lshlrev_b64 v[22:23], 8, v[22:23]
	v_ashrrev_i32_e32 v47, 31, v46
	v_lshl_add_u64 v[22:23], v[34:35], 0, v[22:23]
	v_lshlrev_b64 v[46:47], 8, v[46:47]
	global_store_dword v[22:23], v24, off
	v_lshl_add_u64 v[46:47], v[34:35], 0, v[46:47]
	v_add_u32_e32 v24, 18, v32
	global_store_dword v[46:47], v25, off
	v_ashrrev_i32_e32 v25, 31, v24
	v_add_u32_e32 v48, 19, v32
	v_lshlrev_b64 v[24:25], 8, v[24:25]
	v_ashrrev_i32_e32 v49, 31, v48
	v_lshl_add_u64 v[24:25], v[34:35], 0, v[24:25]
	v_lshlrev_b64 v[48:49], 8, v[48:49]
	global_store_dword v[24:25], v26, off
	v_lshl_add_u64 v[48:49], v[34:35], 0, v[48:49]
	v_add_u32_e32 v26, 24, v32
	global_store_dword v[48:49], v27, off
	v_ashrrev_i32_e32 v27, 31, v26
	v_add_u32_e32 v50, 25, v32
	v_lshlrev_b64 v[26:27], 8, v[26:27]
	v_ashrrev_i32_e32 v51, 31, v50
	v_lshl_add_u64 v[26:27], v[34:35], 0, v[26:27]
	v_lshlrev_b64 v[50:51], 8, v[50:51]
	global_store_dword v[26:27], v28, off
	v_lshl_add_u64 v[50:51], v[34:35], 0, v[50:51]
	v_add_u32_e32 v28, 26, v32
	v_add_u32_e32 v32, 27, v32
	global_store_dword v[50:51], v29, off
	v_ashrrev_i32_e32 v29, 31, v28
	v_ashrrev_i32_e32 v33, 31, v32
	v_lshlrev_b64 v[28:29], 8, v[28:29]
	v_lshlrev_b64 v[32:33], 8, v[32:33]
	v_lshl_add_u64 v[28:29], v[34:35], 0, v[28:29]
	v_lshl_add_u64 v[32:33], v[34:35], 0, v[32:33]
	global_store_dword v[28:29], v30, off
	global_store_dword v[32:33], v31, off
	global_store_dword v[36:37], v0, off offset:128
	global_store_dword v[38:39], v1, off offset:128
	global_store_dword v[16:17], v2, off offset:128
	global_store_dword v[40:41], v3, off offset:128
	global_store_dword v[18:19], v4, off offset:128
	global_store_dword v[42:43], v5, off offset:128
	global_store_dword v[20:21], v6, off offset:128
	global_store_dword v[44:45], v7, off offset:128
	global_store_dword v[22:23], v8, off offset:128
	global_store_dword v[46:47], v9, off offset:128
	global_store_dword v[24:25], v10, off offset:128
	global_store_dword v[48:49], v11, off offset:128
	global_store_dword v[26:27], v12, off offset:128
	global_store_dword v[50:51], v13, off offset:128
	global_store_dword v[28:29], v14, off offset:128
	global_store_dword v[32:33], v15, off offset:128

.LBB0_242:
	s_mul_i32 s37, s60, 0x5000
	s_add_i32 s37, s37, 0
	v_add_u32_e32 v36, s37, v144
	s_waitcnt vmcnt(0)
	s_mov_b64 s[100:101], exec
	s_mov_b64 exec, s[12:13]
	global_load_dword v184, v[174:175], off sc1
	global_load_dword v173, v[176:177], off offset:4 sc1
	s_mov_b64 exec, s[42:43]
	global_atomic_add v221, v[182:183], v181, off sc0
	s_mov_b64 exec, s[100:101]
	s_barrier
	v_add_u32_e32 v32, v36, v151
	ds_read_b128 v[48:51], v32
	ds_read_b128 v[32:35], v32 offset:4096
	v_add_u32_e32 v37, v36, v145
	ds_read_b128 v[64:67], v37
	ds_read_b128 v[52:55], v37 offset:4096
	v_add_u32_e32 v37, v36, v146
	v_add_u32_e32 v36, v36, v147
	ds_read_b128 v[68:71], v37
	ds_read_b128 v[56:59], v37 offset:4096
	ds_read_b128 v[72:75], v36
	ds_read_b128 v[60:63], v36 offset:4096
	s_waitcnt lgkmcnt(6)
	v_mfma_f32_32x32x16_bf16 v[32:47], v[32:35], v[94:97], 0
	s_lshl_b32 s0, s54, 6
	v_add_u32_e32 v130, s33, v116
	s_mov_b32 s1, 0x800000
	s_mov_b32 s72, 0x40c00000
	s_mov_b64 s[66:67], 0x4000
	v_readlane_b32 s73, v254, 13
	s_waitcnt lgkmcnt(4)
	v_mfma_f32_32x32x16_bf16 v[32:47], v[52:55], v[90:93], v[32:47]
	v_add3_u32 v52, s37, v117, v143
	v_add_u32_e32 v131, v52, v142
	ds_read_b64_tr_b16 v[110:111], v131 offset:12288
	ds_read_b64_tr_b16 v[112:113], v131 offset:12800
	ds_read_b64_tr_b16 v[106:107], v131 offset:13312
	ds_read_b64_tr_b16 v[108:109], v131 offset:13824
	ds_read_b64_tr_b16 v[102:103], v131 offset:14336
	ds_read_b64_tr_b16 v[104:105], v131 offset:14848
	ds_read_b64_tr_b16 v[98:99], v131 offset:15360
	ds_read_b64_tr_b16 v[100:101], v131 offset:15872
	s_add_i32 s37, s0, 0xffffff80
	s_addk_i32 s0, 0xffbf
	s_cmp_ge_u32 s0, s33
	s_cselect_b64 s[58:59], -1, 0
	s_waitcnt lgkmcnt(10)
	v_mfma_f32_32x32x16_bf16 v[32:47], v[56:59], v[86:89], v[32:47]
	s_cmp_lt_u32 s0, s33
	s_cselect_b64 s[54:55], -1, 0
	s_cmp_gt_u32 s37, s50
	s_cselect_b64 s[62:63], -1, 0
	s_or_b64 s[54:55], s[54:55], s[62:63]
	s_mov_b64 s[62:63], -1
	s_and_b64 vcc, exec, s[54:55]
	s_waitcnt lgkmcnt(8)
	v_mfma_f32_32x32x16_bf16 v[32:47], v[60:63], v[82:85], v[32:47]
	v_mfma_f32_32x32x16_bf16 v[48:63], v[48:51], v[94:97], 0
	v_mfma_f32_32x32x16_bf16 v[48:63], v[64:67], v[90:93], v[48:63]
	v_mfma_f32_32x32x16_bf16 v[48:63], v[68:71], v[86:89], v[48:63]
	v_mfma_f32_32x32x16_bf16 v[48:63], v[72:75], v[82:85], v[48:63]
	s_cbranch_vccnz .LBB0_244
	v_add_u32_e32 v64, s37, v141
	v_sub_u32_e32 v64, v130, v64
	v_cvt_f32_i32_e32 v64, v64
	s_mov_b32 s0, 0xc2000000
	v_cmp_lt_f32_e32 vcc, 0, v64
	v_add_f32_e32 v65, -1.0, v64
	s_mov_b32 s54, -2.0
	v_cndmask_b32_e32 v66, v137, v115, vcc
	v_mul_f32_e64 v66, |v64|, v66
	v_cmp_lt_f32_e32 vcc, 0, v65
	v_exp_f32_e32 v133, v66
	s_mov_b32 s55, 0xc0400000
	v_cndmask_b32_e32 v66, v137, v115, vcc
	v_mul_f32_e64 v66, |v65|, v66
	v_exp_f32_e32 v134, v66
	v_pk_add_f32 v[66:67], v[64:65], s[0:1] op_sel_hi:[1,0]
	s_mov_b64 s[62:63], 0
	v_cmp_lt_f32_e32 vcc, 0, v66
	s_nop 1
	v_cndmask_b32_e32 v68, v137, v115, vcc
	v_cmp_lt_f32_e32 vcc, 0, v67
	v_mul_f32_e64 v68, |v66|, v68
	v_exp_f32_e32 v68, v68
	v_cndmask_b32_e32 v69, v137, v115, vcc
	v_mul_f32_e64 v69, |v67|, v69
	v_exp_f32_e32 v69, v69
	v_cmp_neq_f32_e32 vcc, 0, v67
	s_nop 1
	v_cndmask_b32_e32 v67, 2.0, v69, vcc
	v_cmp_neq_f32_e32 vcc, 0, v66
	s_nop 1
	v_cndmask_b32_e32 v66, 2.0, v68, vcc
	v_pk_mul_f32 v[116:117], v[32:33], v[66:67]
	v_pk_add_f32 v[66:67], v[64:65], s[54:55] op_sel_hi:[0,1]
	v_cmp_lt_f32_e32 vcc, 0, v66
	s_mov_b32 s54, 0xc1000000
	s_mov_b32 s55, 0xc1100000
	v_cndmask_b32_e32 v68, v137, v115, vcc
	v_mul_f32_e64 v68, |v66|, v68
	v_cmp_lt_f32_e32 vcc, 0, v67
	v_exp_f32_e32 v135, v68
	s_nop 0
	v_cndmask_b32_e32 v68, v137, v115, vcc
	v_mul_f32_e64 v68, |v67|, v68
	v_exp_f32_e32 v141, v68
	v_pk_add_f32 v[68:69], v[66:67], s[0:1] op_sel_hi:[1,0]
	s_nop 0
	v_cmp_lt_f32_e32 vcc, 0, v68
	s_nop 1
	v_cndmask_b32_e32 v70, v137, v115, vcc
	v_cmp_lt_f32_e32 vcc, 0, v69
	v_mul_f32_e64 v70, |v68|, v70
	v_exp_f32_e32 v70, v70
	v_cndmask_b32_e32 v71, v137, v115, vcc
	v_mul_f32_e64 v71, |v69|, v71
	v_exp_f32_e32 v71, v71
	v_cmp_neq_f32_e32 vcc, 0, v69
	s_nop 1
	v_cndmask_b32_e32 v69, 2.0, v71, vcc
	v_cmp_neq_f32_e32 vcc, 0, v68
	s_nop 1
	v_cndmask_b32_e32 v68, 2.0, v70, vcc
	v_pk_mul_f32 v[118:119], v[34:35], v[68:69]
	v_pk_add_f32 v[68:69], v[64:65], s[54:55] op_sel_hi:[0,1]
	v_cmp_lt_f32_e32 vcc, 0, v68
	s_mov_b32 s54, 0xc1200000
	s_mov_b32 s55, 0xc1300000
	v_cndmask_b32_e32 v70, v137, v115, vcc
	v_mul_f32_e64 v70, |v68|, v70
	v_cmp_lt_f32_e32 vcc, 0, v69
	v_exp_f32_e32 v142, v70
	s_nop 0
	v_cndmask_b32_e32 v70, v137, v115, vcc
	v_mul_f32_e64 v70, |v69|, v70
	v_exp_f32_e32 v143, v70
	v_pk_add_f32 v[70:71], v[68:69], s[0:1] op_sel_hi:[1,0]
	s_nop 0
	v_cmp_lt_f32_e32 vcc, 0, v70
	s_nop 1
	v_cndmask_b32_e32 v72, v137, v115, vcc
	v_cmp_lt_f32_e32 vcc, 0, v71
	v_mul_f32_e64 v72, |v70|, v72
	v_exp_f32_e32 v72, v72
	v_cndmask_b32_e32 v73, v137, v115, vcc
	v_mul_f32_e64 v73, |v71|, v73
	v_exp_f32_e32 v73, v73
	v_cmp_neq_f32_e32 vcc, 0, v71
	s_nop 1
	v_cndmask_b32_e32 v71, 2.0, v73, vcc
	v_cmp_neq_f32_e32 vcc, 0, v70
	s_nop 1
	v_cndmask_b32_e32 v70, 2.0, v72, vcc
	v_pk_mul_f32 v[120:121], v[36:37], v[70:71]
	v_pk_add_f32 v[70:71], v[64:65], s[54:55] op_sel_hi:[0,1]
	v_cmp_lt_f32_e32 vcc, 0, v70
	s_mov_b32 s54, 0xc1800000
	s_mov_b32 s55, 0xc1880000
	v_cndmask_b32_e32 v72, v137, v115, vcc
	v_mul_f32_e64 v72, |v70|, v72
	v_cmp_lt_f32_e32 vcc, 0, v71
	v_exp_f32_e32 v144, v72
	s_nop 0
	v_cndmask_b32_e32 v72, v137, v115, vcc
	v_mul_f32_e64 v72, |v71|, v72
	v_exp_f32_e32 v145, v72
	v_pk_add_f32 v[72:73], v[70:71], s[0:1] op_sel_hi:[1,0]
	s_nop 0
	v_cmp_lt_f32_e32 vcc, 0, v72
	s_nop 1
	v_cndmask_b32_e32 v74, v137, v115, vcc
	v_cmp_lt_f32_e32 vcc, 0, v73
	v_mul_f32_e64 v74, |v72|, v74
	v_exp_f32_e32 v74, v74
	v_cndmask_b32_e32 v75, v137, v115, vcc
	v_mul_f32_e64 v75, |v73|, v75
	v_exp_f32_e32 v75, v75
	v_cmp_neq_f32_e32 vcc, 0, v73
	s_nop 1
	v_cndmask_b32_e32 v73, 2.0, v75, vcc
	v_cmp_neq_f32_e32 vcc, 0, v72
	s_nop 1
	v_cndmask_b32_e32 v72, 2.0, v74, vcc
	v_pk_mul_f32 v[122:123], v[38:39], v[72:73]
	v_pk_add_f32 v[72:73], v[64:65], s[54:55] op_sel_hi:[0,1]
	v_cmp_lt_f32_e32 vcc, 0, v72
	s_mov_b32 s54, 0xc1900000
	s_mov_b32 s55, 0xc1980000
	v_cndmask_b32_e32 v74, v137, v115, vcc
	v_mul_f32_e64 v74, |v72|, v74
	v_cmp_lt_f32_e32 vcc, 0, v73
	v_exp_f32_e32 v146, v74
	s_nop 0
	v_cndmask_b32_e32 v74, v137, v115, vcc
	v_mul_f32_e64 v74, |v73|, v74
	v_exp_f32_e32 v147, v74
	v_pk_add_f32 v[74:75], v[72:73], s[0:1] op_sel_hi:[1,0]
	s_nop 0
	v_cmp_lt_f32_e32 vcc, 0, v74
	s_nop 1
	v_cndmask_b32_e32 v76, v137, v115, vcc
	v_cmp_lt_f32_e32 vcc, 0, v75
	v_mul_f32_e64 v76, |v74|, v76
	v_exp_f32_e32 v76, v76
	v_cndmask_b32_e32 v77, v137, v115, vcc
	v_mul_f32_e64 v77, |v75|, v77
	v_exp_f32_e32 v77, v77
	v_cmp_neq_f32_e32 vcc, 0, v75
	s_nop 1
	v_cndmask_b32_e32 v75, 2.0, v77, vcc
	v_cmp_neq_f32_e32 vcc, 0, v74
	s_nop 1
	v_cndmask_b32_e32 v74, 2.0, v76, vcc
	v_pk_mul_f32 v[124:125], v[40:41], v[74:75]
	v_pk_add_f32 v[74:75], v[64:65], s[54:55] op_sel_hi:[0,1]
	v_cmp_lt_f32_e32 vcc, 0, v74
	s_mov_b32 s54, 0xc1c00000
	s_mov_b32 s55, 0xc1c80000
	v_cndmask_b32_e32 v76, v137, v115, vcc
	v_mul_f32_e64 v76, |v74|, v76
	v_cmp_lt_f32_e32 vcc, 0, v75
	v_exp_f32_e32 v151, v76
	s_nop 0
	v_cndmask_b32_e32 v76, v137, v115, vcc
	v_mul_f32_e64 v76, |v75|, v76
	v_exp_f32_e32 v152, v76
	v_pk_add_f32 v[76:77], v[74:75], s[0:1] op_sel_hi:[1,0]
	s_nop 0
	v_cmp_lt_f32_e32 vcc, 0, v76
	s_nop 1
	v_cndmask_b32_e32 v78, v137, v115, vcc
	v_cmp_lt_f32_e32 vcc, 0, v77
	v_mul_f32_e64 v78, |v76|, v78
	v_exp_f32_e32 v78, v78
	v_cndmask_b32_e32 v79, v137, v115, vcc
	v_mul_f32_e64 v79, |v77|, v79
	v_exp_f32_e32 v79, v79
	v_cmp_neq_f32_e32 vcc, 0, v77
	s_nop 1
	v_cndmask_b32_e32 v77, 2.0, v79, vcc
	v_cmp_neq_f32_e32 vcc, 0, v76
	s_nop 1
	v_cndmask_b32_e32 v76, 2.0, v78, vcc
	v_pk_mul_f32 v[126:127], v[42:43], v[76:77]
	v_pk_add_f32 v[76:77], v[64:65], s[54:55] op_sel_hi:[0,1]
	v_cmp_lt_f32_e32 vcc, 0, v76
	s_mov_b32 s54, 0xc1d00000
	s_mov_b32 s55, 0xc1d80000
	v_cndmask_b32_e32 v78, v137, v115, vcc
	v_mul_f32_e64 v78, |v76|, v78
	v_cmp_lt_f32_e32 vcc, 0, v77
	v_exp_f32_e32 v153, v78
	s_nop 0
	v_cndmask_b32_e32 v78, v137, v115, vcc
	v_mul_f32_e64 v78, |v77|, v78
	v_exp_f32_e32 v154, v78
	v_pk_add_f32 v[78:79], v[76:77], s[0:1] op_sel_hi:[1,0]
	s_nop 0
	v_cmp_lt_f32_e32 vcc, 0, v78
	s_nop 1
	v_cndmask_b32_e32 v128, v137, v115, vcc
	v_cmp_lt_f32_e32 vcc, 0, v79
	v_mul_f32_e64 v128, |v78|, v128
	v_exp_f32_e32 v128, v128
	v_cndmask_b32_e32 v129, v137, v115, vcc
	v_mul_f32_e64 v129, |v79|, v129
	v_exp_f32_e32 v129, v129
	v_cmp_neq_f32_e32 vcc, 0, v79
	s_nop 1
	v_cndmask_b32_e32 v79, 2.0, v129, vcc
	v_cmp_neq_f32_e32 vcc, 0, v78
	s_nop 1
	v_cndmask_b32_e32 v78, 2.0, v128, vcc
	v_pk_mul_f32 v[128:129], v[44:45], v[78:79]
	v_pk_add_f32 v[78:79], v[64:65], s[54:55] op_sel_hi:[0,1]
	v_add_f32_e32 v132, 0xc2000000, v78
	v_cmp_lt_f32_e32 vcc, 0, v78
	s_nop 1
	v_cndmask_b32_e32 v155, v137, v115, vcc
	v_cmp_lt_f32_e32 vcc, 0, v132
	v_mul_f32_e64 v155, |v78|, v155
	v_exp_f32_e32 v155, v155
	v_cndmask_b32_e32 v156, v137, v115, vcc
	v_mul_f32_e64 v156, |v132|, v156
	v_exp_f32_e32 v156, v156
	v_cmp_lt_f32_e32 vcc, 0, v79
	s_nop 1
	v_cndmask_b32_e32 v157, v137, v115, vcc
	v_mul_f32_e64 v157, |v79|, v157
	v_exp_f32_e32 v157, v157
	v_cmp_neq_f32_e32 vcc, 0, v132
	s_nop 1
	v_cndmask_b32_e32 v132, 2.0, v156, vcc
	v_add_f32_e32 v156, 0xc2000000, v79
	v_cmp_lt_f32_e32 vcc, 0, v156
	v_mul_f32_e32 v132, v46, v132
	s_nop 0
	v_cndmask_b32_e32 v158, v137, v115, vcc
	v_cmp_neq_f32_e32 vcc, 0, v79
	v_mul_f32_e64 v158, |v156|, v158
	v_exp_f32_e32 v158, v158
	v_cndmask_b32_e32 v79, 2.0, v157, vcc
	v_cmp_neq_f32_e32 vcc, 0, v78
	s_nop 1
	v_cndmask_b32_e32 v78, 2.0, v155, vcc
	v_cmp_neq_f32_e32 vcc, 0, v77
	s_nop 1
	v_cndmask_b32_e32 v77, 2.0, v154, vcc
	v_cmp_neq_f32_e32 vcc, 0, v76
	s_nop 1
	v_cndmask_b32_e32 v76, 2.0, v153, vcc
	v_cmp_neq_f32_e32 vcc, 0, v75
	s_nop 1
	v_cndmask_b32_e32 v75, 2.0, v152, vcc
	v_cmp_neq_f32_e32 vcc, 0, v74
	s_nop 1
	v_cndmask_b32_e32 v74, 2.0, v151, vcc
	v_cmp_neq_f32_e32 vcc, 0, v73
	s_nop 1
	v_cndmask_b32_e32 v73, 2.0, v147, vcc
	v_cmp_neq_f32_e32 vcc, 0, v72
	s_nop 1
	v_cndmask_b32_e32 v72, 2.0, v146, vcc
	v_cmp_neq_f32_e32 vcc, 0, v71
	s_nop 1
	v_cndmask_b32_e32 v71, 2.0, v145, vcc
	v_cmp_neq_f32_e32 vcc, 0, v70
	s_nop 1
	v_cndmask_b32_e32 v70, 2.0, v144, vcc
	v_cmp_neq_f32_e32 vcc, 0, v69
	s_nop 1
	v_cndmask_b32_e32 v69, 2.0, v143, vcc
	v_cmp_neq_f32_e32 vcc, 0, v68
	s_nop 1
	v_cndmask_b32_e32 v68, 2.0, v142, vcc
	v_cmp_neq_f32_e32 vcc, 0, v67
	s_nop 1
	v_cndmask_b32_e32 v67, 2.0, v141, vcc
	v_cmp_neq_f32_e32 vcc, 0, v66
	s_nop 1
	v_cndmask_b32_e32 v66, 2.0, v135, vcc
	v_cmp_neq_f32_e32 vcc, 0, v64
	s_nop 1
	v_cndmask_b32_e32 v64, 2.0, v133, vcc
	v_cmp_neq_f32_e32 vcc, 0, v65
	s_nop 1
	v_cndmask_b32_e32 v65, 2.0, v134, vcc
	v_cmp_neq_f32_e32 vcc, 0, v156
	s_nop 1
	v_cndmask_b32_e32 v133, 2.0, v158, vcc

.LBB0_291:
	s_waitcnt vmcnt(0)
	s_mov_b64 s[100:101], exec
	s_mov_b64 exec, s[12:13]
	global_load_dword v184, v[174:175], off sc1
	global_load_dword v173, v[176:177], off offset:4 sc1
	s_mov_b64 exec, s[42:43]
	global_atomic_add v221, v[182:183], v181, off sc0
	s_mov_b64 exec, s[100:101]
	s_mov_b64 s[44:45], 0

.LBB0_342:
	s_waitcnt vmcnt(0)
	s_mov_b64 s[100:101], exec
	s_mov_b64 exec, s[12:13]
	global_load_dword v184, v[174:175], off sc1
	global_load_dword v173, v[176:177], off offset:4 sc1
	s_mov_b64 exec, s[42:43]
	global_atomic_add v221, v[182:183], v181, off sc0
	s_mov_b64 exec, s[100:101]
	s_mov_b64 s[28:29], 0

.LBB0_365:
	s_and_b32 s73, s72, 31
	s_and_saveexec_b64 s[16:17], s[38:39]
	s_cbranch_execz .LBB0_392
	s_lshl_b32 s0, s73, 2
	v_readlane_b32 s18, v254, 28
	v_readlane_b32 s19, v254, 29
	s_or_b32 s18, s0, s18
	s_ashr_i32 s19, s18, 31
	s_lshl_b64 s[18:19], s[18:19], 2
	v_readlane_b32 s26, v252, 29
	v_readlane_b32 s27, v252, 30
	s_add_u32 s18, s26, s18
	s_addc_u32 s19, s27, s19
	v_mov_b32_e32 v176, s18
	v_mov_b32_e32 v177, s19
	s_cmp_lg_u32 s72, s78
	s_cbranch_scc1 .Lg2_nopre
	v_cmp_lt_u32_e32 vcc, 9, v173
	s_cbranch_vccz .Lg2_nopre
	global_load_dword v192, v81, s[18:19] sc1
	s_branch .LBB0_379
